# k36: k35 + 61 redundant back-to-back s_waitcnt vmcnt ladder entries removed (only the strictest wait of each run kept)
# speedup vs baseline: 1.0099x; 1.0053x over previous
; __device__ __forceinline__ unsigned xb_ld(unsigned* p)              { return __hip_atomic_load(p, __ATOMIC_RELAXED, __HIP_MEMORY_SCOPE_AGENT); }
; __device__ __forceinline__ unsigned xb_add(unsigned* p, unsigned v) { return __hip_atomic_fetch_add(p, v, __ATOMIC_RELAXED, __HIP_MEMORY_SCOPE_AGENT); }
; #define XB_SPIN(cond, bar) do { unsigned _sp = 0; while (cond) { __builtin_amdgcn_s_sleep(1); \
;     if ((++_sp & 255u) == 0u) { if (xb_ld(&(bar)[XB_TMO])) break; if (_sp > XB_SPIN_CAP) { atomicAdd(&(bar)[XB_TMO], 1u); break; } } } } while (0)
; __device__ __forceinline__ void xcd_barrier(const XcdBarrier& b) {
;     ...
;         const unsigned old = xb_add(&bar[XB_XSUB(b.x)], 1u);
;         const unsigned gen = old / nloc;
;         if (old + 1u == (gen + 1u) * nloc) {
;             __builtin_amdgcn_fence(__ATOMIC_RELEASE, "agent");
;             asm volatile("s_waitcnt vmcnt(0)" ::: "memory");
;             const unsigned og = xb_add(&bar[XB_TOP], 1u);
;             const unsigned tg = og / nx;
;             if (og + 1u == (tg + 1u) * nx) xb_add(&bar[XB_TOPGEN], 1u);
;             else XB_SPIN(xb_ld(&bar[XB_TOPGEN]) == tg, bar);
;             __builtin_amdgcn_fence(__ATOMIC_ACQUIRE, "agent");
;             xb_add(&bar[XB_XGEN(b.x)], 1u);
;             asm volatile("s_waitcnt vmcnt(0)" ::: "memory");
;         } else {
;             XB_SPIN(xb_ld(&bar[XB_XGEN(b.x)]) == gen, bar);
;             __builtin_amdgcn_fence(__ATOMIC_ACQUIRE, "agent");
;             asm volatile("s_waitcnt vmcnt(0)" ::: "memory");
.LBB0_76:
	s_or_b64 exec, exec, s[0:1]
	s_waitcnt vmcnt(0)
.LBB0_77:
	s_andn2_saveexec_b64 s[0:1], s[18:19]
	s_cbranch_execz .LBB0_97
	s_mov_b64 s[0:1], exec
	buffer_wbl2 sc1
	s_waitcnt lgkmcnt(0)
	s_waitcnt vmcnt(0)
	buffer_inv sc1
	v_mbcnt_lo_u32_b32 v2, s0, 0
	v_mbcnt_hi_u32_b32 v2, s1, v2
	v_cmp_eq_u32_e32 vcc, 0, v2
	s_and_saveexec_b64 s[12:13], vcc
	s_cbranch_execz .LBB0_80
	s_bcnt1_i32_b64 s0, s[0:1]
	v_mov_b32_e32 v3, 0x7000
	v_mov_b32_e32 v4, s0
	global_atomic_add v3, v3, v4, s[78:79] offset:1024 sc0

; __device__ __forceinline__ unsigned xb_ld(unsigned* p)              { return __hip_atomic_load(p, __ATOMIC_RELAXED, __HIP_MEMORY_SCOPE_AGENT); }
; __device__ __forceinline__ unsigned xb_add(unsigned* p, unsigned v) { return __hip_atomic_fetch_add(p, v, __ATOMIC_RELAXED, __HIP_MEMORY_SCOPE_AGENT); }
; #define XB_SPIN(cond, bar) do { unsigned _sp = 0; while (cond) { __builtin_amdgcn_s_sleep(1); \
;     if ((++_sp & 255u) == 0u) { if (xb_ld(&(bar)[XB_TMO])) break; if (_sp > XB_SPIN_CAP) { atomicAdd(&(bar)[XB_TMO], 1u); break; } } } } while (0)
; __device__ __forceinline__ void xcd_barrier(const XcdBarrier& b) {
;     ...
;         const unsigned old = xb_add(&bar[XB_XSUB(b.x)], 1u);
;         const unsigned gen = old / nloc;
;         if (old + 1u == (gen + 1u) * nloc) {
;             __builtin_amdgcn_fence(__ATOMIC_RELEASE, "agent");
;             asm volatile("s_waitcnt vmcnt(0)" ::: "memory");
;             const unsigned og = xb_add(&bar[XB_TOP], 1u);
;             const unsigned tg = og / nx;
;             if (og + 1u == (tg + 1u) * nx) xb_add(&bar[XB_TOPGEN], 1u);
;             else XB_SPIN(xb_ld(&bar[XB_TOPGEN]) == tg, bar);
;             __builtin_amdgcn_fence(__ATOMIC_ACQUIRE, "agent");
;             xb_add(&bar[XB_XGEN(b.x)], 1u);
;             asm volatile("s_waitcnt vmcnt(0)" ::: "memory");
;         } else {
;             XB_SPIN(xb_ld(&bar[XB_XGEN(b.x)]) == gen, bar);
;             __builtin_amdgcn_fence(__ATOMIC_ACQUIRE, "agent");
;             asm volatile("s_waitcnt vmcnt(0)" ::: "memory");
.LBB0_230:
	s_or_b64 exec, exec, s[0:1]
	s_waitcnt vmcnt(0)
.LBB0_231:
	s_andn2_saveexec_b64 s[0:1], s[18:19]
	s_cbranch_execz .LBB0_251
	s_mov_b64 s[0:1], exec
	buffer_wbl2 sc1
	s_waitcnt lgkmcnt(0)
	s_waitcnt vmcnt(0)
	buffer_inv sc1
	v_mbcnt_lo_u32_b32 v2, s0, 0
	v_mbcnt_hi_u32_b32 v2, s1, v2
	v_cmp_eq_u32_e32 vcc, 0, v2
	s_and_saveexec_b64 s[12:13], vcc
	s_cbranch_execz .LBB0_234
	s_bcnt1_i32_b64 s0, s[0:1]
	v_mov_b32_e32 v3, 0x7000
	v_mov_b32_e32 v4, s0
	global_atomic_add v3, v3, v4, s[78:79] offset:1024 sc0

; __device__ __forceinline__ unsigned xb_ld(unsigned* p)              { return __hip_atomic_load(p, __ATOMIC_RELAXED, __HIP_MEMORY_SCOPE_AGENT); }
; __device__ __forceinline__ void xcd_barrier_complete(unsigned* bar, unsigned x, unsigned& nloc, unsigned& nx) {
;     const unsigned G = gridDim.x * gridDim.y * gridDim.z;
;     unsigned sum, cnt, mine, sp = 0u;
;     for (;;) {
;         sum = 0u; cnt = 0u; mine = 0u;
; #pragma unroll
;         for (unsigned j = 0; j < 16; ++j) { const unsigned c = xb_ld(&bar[XB_XCNT(j)]); sum += c; cnt += (c > 0u) ? 1u : 0u; mine = (j == x) ? c : mine; }
; __device__ __forceinline__ void xcd_barrier(const XcdBarrier& b) {
;     asm volatile("s_waitcnt vmcnt(0)" ::: "memory");
;     __syncthreads();
;     if (threadIdx.x == 0) {
;         unsigned* bar = b.bar;
;         __builtin_amdgcn_s_waitcnt(0);
;         unsigned nloc = b.st[0], nx = b.st[1];
;         if (nloc == 0u) { xcd_barrier_complete(bar, b.x, nloc, nx); b.st[0] = nloc; b.st[1] = nx; }
.LBB0_313:
	s_waitcnt vmcnt(0)
	s_barrier
	s_mov_b64 s[4:5], exec
	v_readlane_b32 s0, v240, 8
	v_readlane_b32 s1, v240, 9
	s_and_b64 s[0:1], s[4:5], s[0:1]
	s_mov_b64 exec, s[0:1]
	s_cbranch_execz .LBB0_365
	s_add_i32 s0, 0, 0x20160
	v_mov_b32_e32 v1, s0
	s_waitcnt vmcnt(0) expcnt(0) lgkmcnt(0)
	ds_read_b32 v3, v1
	s_add_i32 s0, 0, 0x20164
	v_mov_b32_e32 v1, s0
	ds_read_b32 v1, v1
	s_waitcnt lgkmcnt(1)
	v_cmp_ne_u32_e32 vcc, 0, v3
	s_cbranch_vccnz .LBB0_329
	s_add_u32 s6, s78, 0x4200
	s_addc_u32 s7, s79, 0
	s_add_u32 s20, s78, 0x4400
	s_addc_u32 s21, s79, 0
	s_add_u32 s26, s78, 0x4500
	s_addc_u32 s27, s79, 0
	s_add_u32 s28, s78, 0x4600
	s_addc_u32 s29, s79, 0
	s_add_u32 s56, s78, 0x4700
	s_addc_u32 s57, s79, 0
	s_add_u32 s68, s78, 0x4800
	s_addc_u32 s69, s79, 0
	s_add_u32 s80, s78, 0x4900
	s_addc_u32 s81, s79, 0
	s_add_u32 s82, s78, 0x4a00
	s_addc_u32 s83, s79, 0
	s_add_u32 s84, s78, 0x4b00
	s_addc_u32 s85, s79, 0
	s_add_u32 s86, s78, 0x4c00
	s_addc_u32 s87, s79, 0
	s_add_u32 s88, s78, 0x4d00
	s_addc_u32 s89, s79, 0
	s_add_u32 s90, s78, 0x4e00
	s_addc_u32 s91, s79, 0
	s_add_u32 s92, s78, 0x4f00
	s_addc_u32 s93, s79, 0
	s_add_u32 s94, s78, 0x5000
	s_load_dwordx2 s[0:1], s[74:75], 0xf0
	s_load_dword s3, s[74:75], 0xf8
	s_addc_u32 s95, s79, 0
	s_add_u32 s96, s78, 0x5100
	s_addc_u32 s97, s79, 0
	s_add_u32 s12, s78, 0x5200
	s_waitcnt lgkmcnt(0)
	s_mul_i32 s0, s1, s0
	s_addc_u32 s13, s79, 0
	s_mul_i32 s3, s0, s3
	s_add_u32 s0, s78, 0x5300
	s_addc_u32 s1, s79, 0
	s_mov_b32 s74, 1
	v_mov_b32_e32 v17, 0
	s_branch .LBB0_317

; __device__ __forceinline__ unsigned xb_ld(unsigned* p)              { return __hip_atomic_load(p, __ATOMIC_RELAXED, __HIP_MEMORY_SCOPE_AGENT); }
; __device__ __forceinline__ unsigned xb_add(unsigned* p, unsigned v) { return __hip_atomic_fetch_add(p, v, __ATOMIC_RELAXED, __HIP_MEMORY_SCOPE_AGENT); }
; #define XB_SPIN(cond, bar) do { unsigned _sp = 0; while (cond) { __builtin_amdgcn_s_sleep(1); \
;     if ((++_sp & 255u) == 0u) { if (xb_ld(&(bar)[XB_TMO])) break; if (_sp > XB_SPIN_CAP) { atomicAdd(&(bar)[XB_TMO], 1u); break; } } } } while (0)
; __device__ __forceinline__ void xcd_barrier(const XcdBarrier& b) {
;     ...
;         const unsigned old = xb_add(&bar[XB_XSUB(b.x)], 1u);
;         const unsigned gen = old / nloc;
;         if (old + 1u == (gen + 1u) * nloc) {
;             __builtin_amdgcn_fence(__ATOMIC_RELEASE, "agent");
;             asm volatile("s_waitcnt vmcnt(0)" ::: "memory");
;             const unsigned og = xb_add(&bar[XB_TOP], 1u);
;             const unsigned tg = og / nx;
;             if (og + 1u == (tg + 1u) * nx) xb_add(&bar[XB_TOPGEN], 1u);
;             else XB_SPIN(xb_ld(&bar[XB_TOPGEN]) == tg, bar);
;             __builtin_amdgcn_fence(__ATOMIC_ACQUIRE, "agent");
;             xb_add(&bar[XB_XGEN(b.x)], 1u);
;             asm volatile("s_waitcnt vmcnt(0)" ::: "memory");
;         } else {
;             XB_SPIN(xb_ld(&bar[XB_XGEN(b.x)]) == gen, bar);
;             __builtin_amdgcn_fence(__ATOMIC_ACQUIRE, "agent");
;             asm volatile("s_waitcnt vmcnt(0)" ::: "memory");
.LBB0_344:
	s_or_b64 exec, exec, s[0:1]
	s_waitcnt vmcnt(0)
.LBB0_345:
	s_andn2_saveexec_b64 s[0:1], s[20:21]
	s_cbranch_execz .LBB0_365
	s_mov_b64 s[0:1], exec
	buffer_wbl2 sc1
	s_waitcnt lgkmcnt(0)
	s_waitcnt vmcnt(0)
	buffer_inv sc1
	v_mbcnt_lo_u32_b32 v2, s0, 0
	v_mbcnt_hi_u32_b32 v2, s1, v2
	v_cmp_eq_u32_e32 vcc, 0, v2
	s_and_saveexec_b64 s[12:13], vcc
	s_cbranch_execz .LBB0_348
	s_bcnt1_i32_b64 s0, s[0:1]
	v_mov_b32_e32 v3, 0x7000
	v_mov_b32_e32 v4, s0
	global_atomic_add v3, v3, v4, s[78:79] offset:1024 sc0

; __device__ __forceinline__ unsigned xb_ld(unsigned* p)              { return __hip_atomic_load(p, __ATOMIC_RELAXED, __HIP_MEMORY_SCOPE_AGENT); }
; __device__ __forceinline__ unsigned xb_add(unsigned* p, unsigned v) { return __hip_atomic_fetch_add(p, v, __ATOMIC_RELAXED, __HIP_MEMORY_SCOPE_AGENT); }
; #define XB_SPIN(cond, bar) do { unsigned _sp = 0; while (cond) { __builtin_amdgcn_s_sleep(1); \
;     if ((++_sp & 255u) == 0u) { if (xb_ld(&(bar)[XB_TMO])) break; if (_sp > XB_SPIN_CAP) { atomicAdd(&(bar)[XB_TMO], 1u); break; } } } } while (0)
; __device__ __forceinline__ void xcd_barrier(const XcdBarrier& b) {
;     ...
;         const unsigned old = xb_add(&bar[XB_XSUB(b.x)], 1u);
;         const unsigned gen = old / nloc;
;         if (old + 1u == (gen + 1u) * nloc) {
;             __builtin_amdgcn_fence(__ATOMIC_RELEASE, "agent");
;             asm volatile("s_waitcnt vmcnt(0)" ::: "memory");
;             const unsigned og = xb_add(&bar[XB_TOP], 1u);
;             const unsigned tg = og / nx;
;             if (og + 1u == (tg + 1u) * nx) xb_add(&bar[XB_TOPGEN], 1u);
;             else XB_SPIN(xb_ld(&bar[XB_TOPGEN]) == tg, bar);
;             __builtin_amdgcn_fence(__ATOMIC_ACQUIRE, "agent");
;             xb_add(&bar[XB_XGEN(b.x)], 1u);
;             asm volatile("s_waitcnt vmcnt(0)" ::: "memory");
;         } else {
;             XB_SPIN(xb_ld(&bar[XB_XGEN(b.x)]) == gen, bar);
;             __builtin_amdgcn_fence(__ATOMIC_ACQUIRE, "agent");
;             asm volatile("s_waitcnt vmcnt(0)" ::: "memory");
.LBB0_537:
	s_or_b64 exec, exec, s[0:1]
	s_waitcnt vmcnt(0)
.LBB0_538:
	s_andn2_saveexec_b64 s[0:1], s[8:9]
	s_cbranch_execz .LBB0_558
	s_mov_b64 s[0:1], exec
	buffer_wbl2 sc1
	s_waitcnt lgkmcnt(0)
	s_waitcnt vmcnt(0)
	buffer_inv sc1
	v_mbcnt_lo_u32_b32 v2, s0, 0
	v_mbcnt_hi_u32_b32 v2, s1, v2
	v_cmp_eq_u32_e32 vcc, 0, v2
	s_and_saveexec_b64 s[8:9], vcc
	s_cbranch_execz .LBB0_541
	s_bcnt1_i32_b64 s0, s[0:1]
	v_mov_b32_e32 v3, 0x7000
	v_mov_b32_e32 v4, s0
	global_atomic_add v3, v3, v4, s[78:79] offset:1024 sc0

; #define LAS __attribute__((address_space(3)))
; template <int PASS>
; __device__ __forceinline__ void ssd_unit(LAS unsigned char* lds, int ch, int g, const bf16* PROJ, const bf16* XBC, const float* At, const float* DTt, bf16* STS, float* DECS, bf16* OMIX,
;                                          const float* d_skip, const float* ssd_norm) {
;     ...
;         SC[wave * 64 + lane] = v; DL[wave * 64 + lane] = dt;
;         if (lane == (d ? 0 : 63)) TOT[wave] = v;
;     }
;     if (PASS == 0) {
;         { const int n = tid & 63, oct = tid >> 6; const bf16* bp = XBC + (m0 + 8 * oct) * 768 + 512 + 64 * g + n; unsigned vv[8];
; #pragma unroll
;           for (int jj = 0; jj < 8; ++jj) vv[jj] = bp[(size_t)jj * 768];
; #pragma unroll
;           for (int jj = 0; jj < 8; ++jj) asm volatile("" : "+v"(vv[jj]));
;           *(LAS v4u*)(BT + n * RS + oct * 16) = (v4u){vv[0] | (vv[1] << 16), vv[2] | (vv[3] << 16), vv[4] | (vv[5] << 16), vv[6] | (vv[7] << 16)}; }
;         __syncthreads();
;         LAS float* WJ = RED;
;         WJ[tid] = __expf(TOT[tid >> 6] - SC[tid]) * DL[tid];
;         __syncthreads();
;         {
;             const int p = tid & 63, hl = (tid >> 6) & 3, half = tid >> 8; const bf16* xp = XBC + (m0 + 32 * half) * 768 + (4 * g + hl) * 64 + p; float xv[32];
; #pragma unroll
;             for (int jj = 0; jj < 32; ++jj) xv[jj] = bf1(xp[(size_t)jj * 768]);
.LBB0_599:
	s_or_b64 exec, exec, s[4:5]
	s_waitcnt lgkmcnt(0)
	v_lshlrev_b32_e32 v8, 2, v5
	v_lshl_or_b32 v8, s26, 8, v8
	s_and_b64 s[0:1], s[6:7], exec
	v_add_u32_e32 v8, 0, v8
	s_cselect_b32 s0, 63, 0
	v_add_u32_e32 v9, 0x18c00, v8
	v_add_u32_e32 v8, 0x19400, v8
	v_cmp_eq_u32_e32 vcc, s0, v5
	ds_write_b32 v9, v2
	s_waitcnt vmcnt(0)
	ds_write_b32 v8, v7
	s_and_saveexec_b64 s[0:1], vcc
	s_lshl_b32 s3, s26, 2
	s_add_i32 s3, s3, 0
	s_add_i32 s3, s3, 0x19c00
	v_mov_b32_e32 v7, s3
	ds_write_b32 v7, v2
	s_or_b64 exec, exec, s[0:1]
	v_lshlrev_b32_e32 v8, 3, v6
	v_ashrrev_i32_e32 v9, 31, v8
	v_lshl_add_u64 v[8:9], v[8:9], 0, s[42:43]
	v_mov_b64_e32 v[10:11], s[52:53]
	v_mad_u64_u32 v[10:11], s[0:1], v8, s60, v[10:11]
	v_mad_i32_i24 v11, v9, s60, v11
	v_lshlrev_b32_e32 v2, 1, v5
	v_lshl_add_u64 v[8:9], v[10:11], 0, v[2:3]
	s_mov_b64 s[0:1], 0x400
	v_lshl_add_u64 v[10:11], v[8:9], 0, s[0:1]
	global_load_ushort v16, v[8:9], off offset:1024
	global_load_ushort v17, v[8:9], off offset:2560
	global_load_ushort v18, v[10:11], off offset:3072
	v_add_co_u32_e32 v10, vcc, s61, v8
	v_ashrrev_i32_e32 v25, 8, v4
	s_nop 0
	v_addc_co_u32_e32 v11, vcc, 0, v9, vcc
	v_add_co_u32_e32 v8, vcc, s62, v8
	v_lshlrev_b32_e32 v12, 2, v4
	s_nop 0
	v_addc_co_u32_e32 v9, vcc, 0, v9, vcc
	global_load_ushort v19, v[10:11], off offset:1536
	global_load_ushort v20, v[10:11], off offset:3072
	global_load_ushort v21, v[8:9], off offset:512
	global_load_ushort v22, v[8:9], off offset:2048
	global_load_ushort v23, v[8:9], off offset:3584
	v_mul_u32_u24_e32 v8, 0x90, v5
	v_lshlrev_b32_e32 v10, 4, v6
	v_lshl_add_u32 v11, v6, 2, 0
	v_add3_u32 v26, 0, v8, v10
	v_lshlrev_b32_e32 v10, 5, v25
	v_add_u32_e32 v27, 0x19c00, v11
	v_ashrrev_i32_e32 v11, 31, v10
	v_bfe_u32 v24, v4, 6, 2
	v_mov_b64_e32 v[6:7], s[20:21]
	v_lshl_add_u64 v[10:11], v[10:11], 0, s[42:43]
	v_add_u32_e32 v8, 0, v12
	v_add_u32_e32 v28, s64, v12
	v_or_b32_e32 v12, s34, v24
	v_mad_u64_u32 v[6:7], s[0:1], v10, s60, v[6:7]
	v_mov_b32_e32 v9, v3
	v_add_u32_e32 v29, 0x18c00, v8
	v_add_u32_e32 v30, 0x19400, v8
	v_lshlrev_b32_e32 v8, 7, v12
	v_mad_i32_i24 v7, v11, s60, v7
	v_lshl_add_u64 v[6:7], v[6:7], 0, v[8:9]
	v_lshl_add_u64 v[10:11], v[6:7], 0, v[2:3]
	v_mov_b32_e32 v52, v2
	s_nop 0
	v_readfirstlane_b32 s98, v10
	v_readfirstlane_b32 s99, v11
	s_nop 4
	s_movk_i32 s3, 0x6000
	v_lshl_add_u32 v49, v25, 6, 0
	v_lshl_or_b32 v5, v24, 6, v5
	v_mad_u32_u24 v51, v5, s63, v49
	s_waitcnt vmcnt(4)
	v_lshl_or_b32 v6, v17, 16, v16
	s_waitcnt vmcnt(0)
	v_lshl_or_b32 v7, v19, 16, v18
	v_lshl_or_b32 v8, v21, 16, v20
	v_lshl_or_b32 v9, v23, 16, v22
	ds_write_b128 v26, v[6:9] offset:18432
	s_waitcnt lgkmcnt(0)
	s_barrier
	ds_read_b32 v2, v27
	ds_read_b32 v8, v29
	ds_read_b32 v16, v30
	s_waitcnt lgkmcnt(1)
	v_sub_f32_e32 v2, v2, v8
	v_mul_f32_e32 v2, 0x3fb8aa3b, v2
	v_exp_f32_e32 v2, v2
	s_waitcnt lgkmcnt(0)
	v_mul_f32_e32 v2, v16, v2
	ds_write_b32 v28, v2
	s_waitcnt lgkmcnt(0)
	s_barrier
	global_load_ushort v2, v52, s[98:99]
	global_load_ushort v16, v52, s[98:99] offset:1536
	global_load_ushort v18, v52, s[98:99] offset:3072
	s_add_u32 s100, s98, s61
	s_addc_u32 s101, s99, 0
	global_load_ushort v17, v52, s[100:101] offset:512
	global_load_ushort v20, v52, s[100:101] offset:2048
	global_load_ushort v19, v52, s[100:101] offset:3584
	s_add_u32 s90, s98, s62
	s_addc_u32 s91, s99, 0
	global_load_ushort v22, v52, s[90:91] offset:1024
	global_load_ushort v21, v52, s[90:91] offset:2560
	s_add_u32 s4, s98, s65
	s_addc_u32 s5, s99, 0
	global_load_ushort v26, v52, s[4:5]
	global_load_ushort v23, v52, s[4:5] offset:1536
	s_add_u32 s6, s98, s66
	s_addc_u32 s7, s99, 0
	global_load_ushort v27, v52, s[6:7] offset:512
	s_waitcnt vmcnt(7)
	v_lshlrev_b32_e32 v17, 16, v17
	s_waitcnt vmcnt(5)
	v_lshlrev_b32_e32 v19, 16, v19
	global_load_ushort v28, v52, s[4:5] offset:3072
	global_load_ushort v29, v52, s[6:7] offset:3584
	s_add_u32 s8, s98, s67
	s_addc_u32 s9, s99, 0
	global_load_ushort v30, v52, s[8:9] offset:1024
	global_load_ushort v31, v52, s[8:9] offset:2560
	s_add_u32 s100, s98, s3
	s_addc_u32 s101, s99, 0
	global_load_ushort v32, v52, s[100:101]
	global_load_ushort v33, v52, s[100:101] offset:1536
	global_load_ushort v34, v52, s[100:101] offset:3072
	global_load_ushort v35, v52, s[6:7] offset:2048
	v_lshlrev_b32_e32 v15, 16, v16
	s_add_u32 s90, s98, s68
	s_addc_u32 s91, s99, 0
	global_load_ushort v36, v52, s[90:91] offset:512
	global_load_ushort v37, v52, s[90:91] offset:2048
	global_load_ushort v38, v52, s[90:91] offset:3584
	v_lshlrev_b32_e32 v14, 16, v2
	s_add_u32 s4, s98, s69
	s_addc_u32 s5, s99, 0
	global_load_ushort v39, v52, s[4:5] offset:1024
	global_load_ushort v40, v52, s[4:5] offset:2560
	v_lshlrev_b32_e32 v16, 16, v18
	s_add_u32 s6, s98, s70
	s_addc_u32 s7, s99, 0
	global_load_ushort v41, v52, s[6:7]
	global_load_ushort v42, v52, s[6:7] offset:1536
	global_load_ushort v43, v52, s[6:7] offset:3072
	s_add_u32 s8, s98, s71
	s_addc_u32 s9, s99, 0
	global_load_ushort v44, v52, s[8:9] offset:512
	global_load_ushort v45, v52, s[8:9] offset:2048
	global_load_ushort v46, v52, s[8:9] offset:3584
	v_lshlrev_b32_e32 v18, 16, v20
	s_add_u32 s100, s98, s72
	s_addc_u32 s101, s99, 0
	global_load_ushort v47, v52, s[100:101] offset:1024
	global_load_ushort v48, v52, s[100:101] offset:2560
	v_lshlrev_b32_e32 v6, 7, v25
	v_lshlrev_b32_e32 v7, 8, v24
	v_add3_u32 v50, s64, v6, v7
	ds_read_b128 v[6:9], v50
	ds_read_b128 v[10:13], v50 offset:16
	s_waitcnt vmcnt(24)
; #define LAS __attribute__((address_space(3)))
; __device__ __forceinline__ unsigned pk2(float lo, float hi) { const f32x2cv v = {lo, hi}; const bf16x2cv b = __builtin_convertvector(v, bf16x2cv); return __builtin_bit_cast(unsigned, b); }
; template <int PASS>
; __device__ __forceinline__ void ssd_unit(LAS unsigned char* lds, int ch, int g, const bf16* PROJ, const bf16* XBC, const float* At, const float* DTt, bf16* STS, float* DECS, bf16* OMIX,
;                                          const float* d_skip, const float* ssd_norm) {
;     ...
;             const int p = tid & 63, hl = (tid >> 6) & 3, half = tid >> 8; const bf16* xp = XBC + (m0 + 32 * half) * 768 + (4 * g + hl) * 64 + p; float xv[32];
; #pragma unroll
;             for (int jj = 0; jj < 32; ++jj) xv[jj] = bf1(xp[(size_t)jj * 768]);
; #pragma unroll
;             for (int d = 0; d < 2; ++d) { const LAS f32x4* wj = (const LAS f32x4*)(WJ + (d * 4 + hl) * 64 + 32 * half);
;                 LAS unsigned char* dst = XT + ((d * 4 + hl) * 64 + p) * RS + half * 64;
; #pragma unroll
;                 for (int o8 = 0; o8 < 4; ++o8) { unsigned pk[4];
;                     const f32x4 wa = wj[2 * o8], wb = wj[2 * o8 + 1];
;                     pk[0] = pk2(xv[8 * o8] * wa.x, xv[8 * o8 + 1] * wa.y); pk[1] = pk2(xv[8 * o8 + 2] * wa.z, xv[8 * o8 + 3] * wa.w); pk[2] = pk2(xv[8 * o8 + 4] * wb.x, xv[8 * o8 + 5] * wb.y); pk[3] = pk2(xv[8 * o8 + 6] * wb.z, xv[8 * o8 + 7] * wb.w);
;                     *(LAS v4u*)(dst + o8 * 16) = (v4u){pk[0], pk[1], pk[2], pk[3]}; } }
;             if (tid < 8) DECS[(size_t)(ch * 2 + (tid >> 2)) * 8 + 4 * g + (tid & 3)] = __expf(TOT[tid]);
	v_lshlrev_b32_e32 v21, 16, v21
	v_lshlrev_b32_e32 v20, 16, v22
	s_waitcnt vmcnt(22)
	v_lshlrev_b32_e32 v23, 16, v23
	s_waitcnt lgkmcnt(1)
	v_pk_mul_f32 v[6:7], v[6:7], v[14:15]
	v_pk_mul_f32 v[8:9], v[8:9], v[16:17]
	s_waitcnt lgkmcnt(0)
	v_pk_mul_f32 v[10:11], v[10:11], v[18:19]
	v_pk_mul_f32 v[12:13], v[12:13], v[20:21]
	v_cvt_pk_bf16_f32 v6, v6, v7
	v_cvt_pk_bf16_f32 v7, v8, v9
	v_cvt_pk_bf16_f32 v8, v10, v11
	v_cvt_pk_bf16_f32 v9, v12, v13
	ds_write_b128 v51, v[6:9] offset:27648
	ds_read_b128 v[6:9], v50 offset:32
	ds_read_b128 v[10:13], v50 offset:48
	v_lshlrev_b32_e32 v22, 16, v26
	s_waitcnt vmcnt(21)
	v_lshlrev_b32_e32 v25, 16, v27
	v_or_b32_e32 v2, 0x100, v5
	s_waitcnt lgkmcnt(1)
	v_pk_mul_f32 v[6:7], v[6:7], v[22:23]
	v_mad_u32_u24 v2, v2, s63, v49
	v_cvt_pk_bf16_f32 v6, v6, v7
	v_cmp_gt_i32_e32 vcc, 8, v4
	s_waitcnt vmcnt(20)
	v_lshlrev_b32_e32 v24, 16, v28
	s_waitcnt vmcnt(19)
	v_lshlrev_b32_e32 v27, 16, v29
	v_pk_mul_f32 v[8:9], v[8:9], v[24:25]
	s_waitcnt vmcnt(17)
	v_lshlrev_b32_e32 v29, 16, v31
	v_lshlrev_b32_e32 v28, 16, v30
	v_cvt_pk_bf16_f32 v7, v8, v9
	s_waitcnt vmcnt(15)
	v_lshlrev_b32_e32 v31, 16, v33
	s_waitcnt vmcnt(13)
	v_lshlrev_b32_e32 v26, 16, v35
	s_waitcnt lgkmcnt(0)
	v_pk_mul_f32 v[10:11], v[10:11], v[26:27]
	v_lshlrev_b32_e32 v30, 16, v32
	v_cvt_pk_bf16_f32 v8, v10, v11
	v_pk_mul_f32 v[10:11], v[12:13], v[28:29]
	s_waitcnt vmcnt(12)
	v_lshlrev_b32_e32 v33, 16, v36
	v_cvt_pk_bf16_f32 v9, v10, v11
	ds_write_b128 v51, v[6:9] offset:27664
	ds_read_b128 v[6:9], v50 offset:64
	ds_read_b128 v[10:13], v50 offset:80
	v_lshlrev_b32_e32 v32, 16, v34
	s_waitcnt vmcnt(10)
	v_lshlrev_b32_e32 v35, 16, v38
	v_lshlrev_b32_e32 v34, 16, v37
	s_waitcnt lgkmcnt(1)
	v_pk_mul_f32 v[6:7], v[6:7], v[30:31]
	v_pk_mul_f32 v[8:9], v[8:9], v[32:33]
	s_waitcnt vmcnt(8)
	v_lshlrev_b32_e32 v37, 16, v40
	v_lshlrev_b32_e32 v36, 16, v39
	v_cvt_pk_bf16_f32 v6, v6, v7
	v_cvt_pk_bf16_f32 v7, v8, v9
	s_waitcnt lgkmcnt(0)
	v_pk_mul_f32 v[8:9], v[10:11], v[34:35]
	v_pk_mul_f32 v[10:11], v[12:13], v[36:37]
	v_cvt_pk_bf16_f32 v8, v8, v9
	v_cvt_pk_bf16_f32 v9, v10, v11
	ds_write_b128 v51, v[6:9] offset:27680
	ds_read_b128 v[6:9], v50 offset:96
	ds_read_b128 v[10:13], v50 offset:112
	s_waitcnt vmcnt(6)
	v_lshlrev_b32_e32 v39, 16, v42
	v_lshlrev_b32_e32 v38, 16, v41
	s_waitcnt vmcnt(4)
	v_lshlrev_b32_e32 v41, 16, v44
	v_lshlrev_b32_e32 v40, 16, v43
	s_waitcnt lgkmcnt(1)
	v_pk_mul_f32 v[6:7], v[6:7], v[38:39]
	v_pk_mul_f32 v[8:9], v[8:9], v[40:41]
	s_waitcnt vmcnt(2)
	v_lshlrev_b32_e32 v43, 16, v46
	v_lshlrev_b32_e32 v42, 16, v45
	s_waitcnt vmcnt(0)
	v_lshlrev_b32_e32 v45, 16, v48
	v_lshlrev_b32_e32 v44, 16, v47
	v_cvt_pk_bf16_f32 v6, v6, v7
	v_cvt_pk_bf16_f32 v7, v8, v9
	s_waitcnt lgkmcnt(0)
	v_pk_mul_f32 v[8:9], v[10:11], v[42:43]
	v_pk_mul_f32 v[10:11], v[12:13], v[44:45]
	v_cvt_pk_bf16_f32 v8, v8, v9
	v_cvt_pk_bf16_f32 v9, v10, v11
	ds_write_b128 v51, v[6:9] offset:27696
	ds_read_b128 v[6:9], v50 offset:1024
	ds_read_b128 v[10:13], v50 offset:1040
	s_waitcnt lgkmcnt(1)
	v_pk_mul_f32 v[6:7], v[6:7], v[14:15]
	v_pk_mul_f32 v[8:9], v[8:9], v[16:17]
	v_cvt_pk_bf16_f32 v6, v6, v7
	v_cvt_pk_bf16_f32 v7, v8, v9
	s_waitcnt lgkmcnt(0)
	v_pk_mul_f32 v[8:9], v[10:11], v[18:19]
	v_pk_mul_f32 v[10:11], v[12:13], v[20:21]
	v_cvt_pk_bf16_f32 v8, v8, v9
	v_cvt_pk_bf16_f32 v9, v10, v11
	ds_write_b128 v2, v[6:9] offset:27648
	ds_read_b128 v[6:9], v50 offset:1056
	ds_read_b128 v[10:13], v50 offset:1072
	s_waitcnt lgkmcnt(1)
	v_pk_mul_f32 v[6:7], v[6:7], v[22:23]
	v_pk_mul_f32 v[8:9], v[8:9], v[24:25]
	v_cvt_pk_bf16_f32 v6, v6, v7
	v_cvt_pk_bf16_f32 v7, v8, v9
	s_waitcnt lgkmcnt(0)
	v_pk_mul_f32 v[8:9], v[10:11], v[26:27]
	v_pk_mul_f32 v[10:11], v[12:13], v[28:29]
	v_cvt_pk_bf16_f32 v8, v8, v9
	v_cvt_pk_bf16_f32 v9, v10, v11
	ds_write_b128 v2, v[6:9] offset:27664
	ds_read_b128 v[6:9], v50 offset:1088
	ds_read_b128 v[10:13], v50 offset:1104
	s_waitcnt lgkmcnt(1)
	v_pk_mul_f32 v[6:7], v[6:7], v[30:31]
	v_pk_mul_f32 v[8:9], v[8:9], v[32:33]
	v_cvt_pk_bf16_f32 v6, v6, v7
	v_cvt_pk_bf16_f32 v7, v8, v9
	s_waitcnt lgkmcnt(0)
	v_pk_mul_f32 v[8:9], v[10:11], v[34:35]
	v_pk_mul_f32 v[10:11], v[12:13], v[36:37]
	v_cvt_pk_bf16_f32 v8, v8, v9
	v_cvt_pk_bf16_f32 v9, v10, v11
	ds_write_b128 v2, v[6:9] offset:27680
	ds_read_b128 v[6:9], v50 offset:1120
	ds_read_b128 v[10:13], v50 offset:1136
	s_waitcnt lgkmcnt(1)
	v_pk_mul_f32 v[6:7], v[6:7], v[38:39]
	v_pk_mul_f32 v[8:9], v[8:9], v[40:41]
	v_cvt_pk_bf16_f32 v6, v6, v7
	v_cvt_pk_bf16_f32 v7, v8, v9
	s_waitcnt lgkmcnt(0)
	v_pk_mul_f32 v[8:9], v[10:11], v[42:43]
	v_pk_mul_f32 v[10:11], v[12:13], v[44:45]
	v_cvt_pk_bf16_f32 v8, v8, v9
	v_cvt_pk_bf16_f32 v9, v10, v11
	ds_write_b128 v2, v[6:9] offset:27696
	s_and_saveexec_b64 s[0:1], vcc
	s_cbranch_execz .LBB0_603
	v_lshl_add_u32 v2, v4, 2, 0
	v_add_u32_e32 v2, 0x19c00, v2
	ds_read_b32 v2, v2
	s_and_b32 s3, s27, -2
	v_ashrrev_i32_e32 v5, 2, v4
	v_add_u32_e32 v6, s3, v5
	v_ashrrev_i32_e32 v7, 31, v6
	s_waitcnt lgkmcnt(0)
	v_mul_f32_e32 v2, 0x3fb8aa3b, v2
	v_exp_f32_e32 v5, v2
	v_and_b32_e32 v2, 3, v4
	v_lshlrev_b64 v[6:7], 5, v[6:7]
	v_lshl_add_u64 v[6:7], s[40:41], 0, v[6:7]
	v_lshlrev_b32_e32 v2, 2, v2
	v_lshl_add_u64 v[6:7], v[6:7], 0, v[2:3]
	s_lshl_b32 s42, s34, 2
	v_lshl_add_u64 v[6:7], v[6:7], 0, s[42:43]
	global_store_dword v[6:7], v5, off

; #define LAS __attribute__((address_space(3)))
; template <int PASS>
; __device__ __forceinline__ void gla_unit(LAS unsigned char* lds, int ch, int h, const bf16* PROJ, const bf16* GT, bf16* STG, float* DECG, bf16* OMIX, const float* gla_norm) {
;     ...
;         OFFS[(d * 4 + qt) * 64 + kk] = d ? c[0] : c[15];
;         { const int vcol = tid & 127, q4 = tid >> 7; const bf16* vp = PROJ + (m0 + 16 * q4) * LDP + PV + h * 128 + vcol; unsigned vv[16];
; #pragma unroll
;           for (int jj = 0; jj < 16; ++jj) vv[jj] = vp[(size_t)jj * LDP];
; #pragma unroll
;           for (int jj = 0; jj < 16; ++jj) asm volatile("" : "+v"(vv[jj]));
;           v4u w0, w1; w0.x = vv[0] | (vv[1] << 16); w0.y = vv[2] | (vv[3] << 16); w0.z = vv[4] | (vv[5] << 16); w0.w = vv[6] | (vv[7] << 16);
;           w1.x = vv[8] | (vv[9] << 16); w1.y = vv[10] | (vv[11] << 16); w1.z = vv[12] | (vv[13] << 16); w1.w = vv[14] | (vv[15] << 16);
;           *(LAS v4u*)(VT + vcol * RS + q4 * 32) = w0; *(LAS v4u*)(VT + vcol * RS + q4 * 32 + 16) = w1; }
;         __syncthreads();
;         float off = 0.f, tot = 0.f;
; #pragma unroll
;         for (int q2 = 0; q2 < 4; ++q2) { const float t = OFFS[(d * 4 + q2) * 64 + kk]; tot += t; if (d ? (q2 > qt) : (q2 < qt)) off += t; }
.LBB0_609:
	s_or_b64 exec, exec, s[0:1]
	v_ashrrev_i32_e32 v7, 7, v48
	v_lshlrev_b32_e32 v36, 4, v7
	v_ashrrev_i32_e32 v37, 31, v36
	v_lshl_add_u64 v[36:37], s[6:7], 0, v[36:37]
	v_mov_b64_e32 v[38:39], s[56:57]
	v_and_b32_e32 v5, 0x7f, v48
	v_mad_u64_u32 v[38:39], s[0:1], v36, s73, v[38:39]
	v_mad_i32_i24 v39, v37, s73, v39
	v_lshlrev_b32_e32 v2, 1, v5
	v_lshl_add_u64 v[36:37], v[38:39], 0, v[2:3]
	s_nop 0
	v_readfirstlane_b32 s90, v36
	v_readfirstlane_b32 s91, v37
	s_nop 4
	s_mov_b32 s0, 0x15000
	global_load_ushort v2, v158, s[90:91] offset:1024
	s_add_u32 s98, s90, s61
	s_addc_u32 s99, s91, 0
	global_load_ushort v8, v158, s[98:99] offset:2688
	s_add_u32 s100, s90, s65
	s_addc_u32 s101, s91, 0
	global_load_ushort v11, v158, s[100:101] offset:256
	s_add_u32 s98, s90, s66
	s_addc_u32 s99, s91, 0
	global_load_ushort v13, v158, s[98:99] offset:1920
	s_add_u32 s100, s90, s67
	s_addc_u32 s101, s91, 0
	global_load_ushort v15, v158, s[100:101] offset:3584
	s_add_u32 s98, s90, s68
	s_addc_u32 s99, s91, 0
	global_load_ushort v17, v158, s[98:99] offset:1152
	s_add_u32 s100, s90, s69
	s_addc_u32 s101, s91, 0
	global_load_ushort v19, v158, s[100:101] offset:2816
	s_add_u32 s98, s90, s71
	s_addc_u32 s99, s91, 0
	global_load_ushort v21, v158, s[98:99] offset:384
	s_add_u32 s8, s90, s0
	s_addc_u32 s9, s91, 0
	s_mov_b64 s[0:1], 0
	s_add_u32 s100, s90, s72
	s_addc_u32 s101, s91, 0
	global_load_ushort v23, v158, s[100:101] offset:2048
	s_add_u32 s98, s90, s74
	s_addc_u32 s99, s91, 0
	global_load_ushort v25, v158, s[98:99] offset:3712
	s_add_u32 s100, s90, s75
	s_addc_u32 s101, s91, 0
	global_load_ushort v27, v158, s[100:101] offset:1280
	s_add_u32 s98, s90, s80
	s_addc_u32 s99, s91, 0
	global_load_ushort v29, v158, s[98:99] offset:2944
	s_add_u32 s100, s90, s81
	s_addc_u32 s101, s91, 0
	global_load_ushort v31, v158, s[100:101] offset:512
	s_add_u32 s98, s90, s82
	s_addc_u32 s99, s91, 0
	global_load_ushort v33, v158, s[98:99] offset:2176
	s_add_u32 s100, s90, s83
	s_addc_u32 s101, s91, 0
	global_load_ushort v35, v158, s[100:101] offset:3840
	global_load_ushort v37, v158, s[8:9] offset:1408
	v_lshlrev_b32_e32 v46, 10, v49
	v_lshlrev_b32_e32 v39, 8, v51
	v_add_u32_e32 v40, s85, v46
	v_lshlrev_b32_e32 v36, 2, v50
	v_cndmask_b32_e32 v38, v9, v6, vcc
	v_add3_u32 v39, v40, v39, v36
	ds_write_b32 v39, v38
	s_waitcnt vmcnt(9)
	v_lshl_or_b32 v38, v8, 16, v2
	v_mul_u32_u24_e32 v2, 0x90, v5
	v_lshlrev_b32_e32 v5, 5, v7
	s_waitcnt vmcnt(8)
	v_lshl_or_b32 v39, v13, 16, v11
	v_lshl_or_b32 v40, v17, 16, v15
	v_lshl_or_b32 v41, v21, 16, v19
	v_add3_u32 v2, 0, v2, v5
	s_waitcnt vmcnt(0)
	v_lshl_or_b32 v42, v25, 16, v23
	v_lshl_or_b32 v43, v29, 16, v27
	v_lshl_or_b32 v44, v33, 16, v31
	v_lshl_or_b32 v45, v37, 16, v35
	ds_write_b128 v2, v[38:41] offset:55296
	ds_write_b128 v2, v[42:45] offset:55312
	v_add_u32_e32 v2, s85, v36
	v_add_u32_e32 v2, v2, v46
	s_waitcnt lgkmcnt(0)
	s_barrier
	ds_read2st64_b32 v[38:39], v2 offset1:1
	v_cmp_eq_u32_e64 s[6:7], 0, v51
	s_and_saveexec_b64 s[8:9], s[4:5]
	s_xor_b64 s[12:13], exec, s[8:9]
	v_cmp_lt_u32_e64 s[8:9], 1, v51
	s_and_b64 s[0:1], s[8:9], exec
	s_or_saveexec_b64 s[8:9], s[12:13]
	s_waitcnt lgkmcnt(0)
	v_add_f32_e32 v7, 0, v38
	s_or_b64 s[12:13], vcc, s[6:7]
	v_cndmask_b32_e64 v8, v7, 0, s[12:13]
	v_mov_b32_e32 v5, v8
	s_xor_b64 exec, exec, s[8:9]
	s_andn2_b64 s[0:1], s[0:1], exec
	s_and_b64 s[12:13], s[6:7], exec
	v_mov_b32_e32 v5, 0
	s_or_b64 s[0:1], s[0:1], s[12:13]
	s_or_b64 exec, exec, s[8:9]
	s_and_saveexec_b64 s[8:9], s[0:1]
	v_add_f32_e32 v5, v39, v8
	s_or_b64 exec, exec, s[8:9]
	ds_read_b32 v8, v2 offset:512
	s_mov_b64 s[0:1], 0
	v_cmp_eq_u32_e64 s[8:9], 3, v51
	s_and_saveexec_b64 s[12:13], s[4:5]
	s_xor_b64 s[4:5], exec, s[12:13]
	s_cbranch_execnz .LBB0_621
	s_andn2_saveexec_b64 s[8:9], s[4:5]
	s_cbranch_execnz .LBB0_622

; __device__ __forceinline__ unsigned xb_ld(unsigned* p)              { return __hip_atomic_load(p, __ATOMIC_RELAXED, __HIP_MEMORY_SCOPE_AGENT); }
; __device__ __forceinline__ unsigned xb_add(unsigned* p, unsigned v) { return __hip_atomic_fetch_add(p, v, __ATOMIC_RELAXED, __HIP_MEMORY_SCOPE_AGENT); }
; #define XB_SPIN(cond, bar) do { unsigned _sp = 0; while (cond) { __builtin_amdgcn_s_sleep(1); \
;     if ((++_sp & 255u) == 0u) { if (xb_ld(&(bar)[XB_TMO])) break; if (_sp > XB_SPIN_CAP) { atomicAdd(&(bar)[XB_TMO], 1u); break; } } } } while (0)
; __device__ __forceinline__ void xcd_barrier(const XcdBarrier& b) {
;     ...
;             __builtin_amdgcn_fence(__ATOMIC_RELEASE, "agent");
;             asm volatile("s_waitcnt vmcnt(0)" ::: "memory");
;             const unsigned og = xb_add(&bar[XB_TOP], 1u);
;             const unsigned tg = og / nx;
;             if (og + 1u == (tg + 1u) * nx) xb_add(&bar[XB_TOPGEN], 1u);
;             else XB_SPIN(xb_ld(&bar[XB_TOPGEN]) == tg, bar);
;             __builtin_amdgcn_fence(__ATOMIC_ACQUIRE, "agent");
;             xb_add(&bar[XB_XGEN(b.x)], 1u);
;             asm volatile("s_waitcnt vmcnt(0)" ::: "memory");
;         } else {
;             XB_SPIN(xb_ld(&bar[XB_XGEN(b.x)]) == gen, bar);
;             __builtin_amdgcn_fence(__ATOMIC_ACQUIRE, "agent");
;             asm volatile("s_waitcnt vmcnt(0)" ::: "memory");
.LBB0_654:
	s_or_b64 exec, exec, s[0:1]
	s_waitcnt vmcnt(0)
.LBB0_655:
	s_andn2_saveexec_b64 s[0:1], s[8:9]
	s_cbranch_execz .LBB0_675
	s_mov_b64 s[0:1], exec
	buffer_wbl2 sc1
	s_waitcnt lgkmcnt(0)
	s_waitcnt vmcnt(0)
	buffer_inv sc1
	v_mbcnt_lo_u32_b32 v2, s0, 0
	v_mbcnt_hi_u32_b32 v2, s1, v2
	v_cmp_eq_u32_e32 vcc, 0, v2
	s_and_saveexec_b64 s[8:9], vcc
	s_cbranch_execz .LBB0_658
	s_bcnt1_i32_b64 s0, s[0:1]
	v_mov_b32_e32 v3, 0x7000
	v_mov_b32_e32 v4, s0
	global_atomic_add v3, v3, v4, s[78:79] offset:1024 sc0

; __device__ __forceinline__ unsigned xb_ld(unsigned* p)              { return __hip_atomic_load(p, __ATOMIC_RELAXED, __HIP_MEMORY_SCOPE_AGENT); }
; __device__ __forceinline__ unsigned xb_add(unsigned* p, unsigned v) { return __hip_atomic_fetch_add(p, v, __ATOMIC_RELAXED, __HIP_MEMORY_SCOPE_AGENT); }
; #define XB_SPIN(cond, bar) do { unsigned _sp = 0; while (cond) { __builtin_amdgcn_s_sleep(1); \
;     if ((++_sp & 255u) == 0u) { if (xb_ld(&(bar)[XB_TMO])) break; if (_sp > XB_SPIN_CAP) { atomicAdd(&(bar)[XB_TMO], 1u); break; } } } } while (0)
; __device__ __forceinline__ void xcd_barrier(const XcdBarrier& b) {
;     ...
;             __builtin_amdgcn_fence(__ATOMIC_RELEASE, "agent");
;             asm volatile("s_waitcnt vmcnt(0)" ::: "memory");
;             const unsigned og = xb_add(&bar[XB_TOP], 1u);
;             const unsigned tg = og / nx;
;             if (og + 1u == (tg + 1u) * nx) xb_add(&bar[XB_TOPGEN], 1u);
;             else XB_SPIN(xb_ld(&bar[XB_TOPGEN]) == tg, bar);
;             __builtin_amdgcn_fence(__ATOMIC_ACQUIRE, "agent");
;             xb_add(&bar[XB_XGEN(b.x)], 1u);
;             asm volatile("s_waitcnt vmcnt(0)" ::: "memory");
;         } else {
;             XB_SPIN(xb_ld(&bar[XB_XGEN(b.x)]) == gen, bar);
;             __builtin_amdgcn_fence(__ATOMIC_ACQUIRE, "agent");
;             asm volatile("s_waitcnt vmcnt(0)" ::: "memory");
.LBB0_736:
	s_or_b64 exec, exec, s[0:1]
	s_waitcnt vmcnt(0)
.LBB0_737:
	s_andn2_saveexec_b64 s[0:1], s[8:9]
	s_cbranch_execz .LBB0_757
	s_mov_b64 s[0:1], exec
	buffer_wbl2 sc1
	s_waitcnt lgkmcnt(0)
	s_waitcnt vmcnt(0)
	buffer_inv sc1
	v_mbcnt_lo_u32_b32 v2, s0, 0
	v_mbcnt_hi_u32_b32 v2, s1, v2
	v_cmp_eq_u32_e32 vcc, 0, v2
	s_and_saveexec_b64 s[8:9], vcc
	s_cbranch_execz .LBB0_740
	s_bcnt1_i32_b64 s0, s[0:1]
	v_mov_b32_e32 v3, 0x7000
	v_mov_b32_e32 v4, s0
	global_atomic_add v3, v3, v4, s[78:79] offset:1024 sc0

; template <int PASS>
; __device__ __forceinline__ void ssd_unit(LAS unsigned char* lds, int ch, int g, const bf16* PROJ, const bf16* XBC, const float* At, const float* DTt, bf16* STS, float* DECS, bf16* OMIX,
;                                          const float* d_skip, const float* ssd_norm) {
;     ...
;         const int d = wave >> 2, hl = wave & 3; const size_t ix = ((size_t)d * MALL + m0 + lane) * 8 + 4 * g + hl;
;         float v = At[ix]; const float dt = DTt[ix];
; #pragma unroll
;         for (int o = 1; o < 64; o <<= 1) { const float t = bperm(v, d ? lane + o : lane - o); if (d ? (lane + o < 64) : (lane >= o)) v += t; }
;         SC[wave * 64 + lane] = v; DL[wave * 64 + lane] = dt;
;         if (lane == (d ? 0 : 63)) TOT[wave] = v;
;     }
;     if (PASS == 0) {
;         { const int n = tid & 63, oct = tid >> 6; const bf16* bp = XBC + (m0 + 8 * oct) * 768 + 512 + 64 * g + n; unsigned vv[8];
; #pragma unroll
;           for (int jj = 0; jj < 8; ++jj) vv[jj] = bp[(size_t)jj * 768];
; #pragma unroll
;           for (int jj = 0; jj < 8; ++jj) asm volatile("" : "+v"(vv[jj]));
;           *(LAS v4u*)(BT + n * RS + oct * 16) = (v4u){vv[0] | (vv[1] << 16), vv[2] | (vv[3] << 16), vv[4] | (vv[5] << 16), vv[6] | (vv[7] << 16)}; }
;         __syncthreads();
;         LAS float* WJ = RED;
;         WJ[tid] = __expf(TOT[tid >> 6] - SC[tid]) * DL[tid];
;         __syncthreads();
;         {
;             const int p = tid & 63, hl = (tid >> 6) & 3, half = tid >> 8; const bf16* xp = XBC + (m0 + 32 * half) * 768 + (4 * g + hl) * 64 + p; float xv[32];
; #pragma unroll
;             for (int jj = 0; jj < 32; ++jj) xv[jj] = bf1(xp[(size_t)jj * 768]);
; #pragma unroll
;             for (int d = 0; d < 2; ++d) { const LAS f32x4* wj = (const LAS f32x4*)(WJ + (d * 4 + hl) * 64 + 32 * half);
;                 LAS unsigned char* dst = XT + ((d * 4 + hl) * 64 + p) * RS + half * 64;
; #pragma unroll
;                 for (int o8 = 0; o8 < 4; ++o8) { unsigned pk[4];
;                     const f32x4 wa = wj[2 * o8], wb = wj[2 * o8 + 1];
;                     pk[0] = pk2(xv[8 * o8] * wa.x, xv[8 * o8 + 1] * wa.y); pk[1] = pk2(xv[8 * o8 + 2] * wa.z, xv[8 * o8 + 3] * wa.w); pk[2] = pk2(xv[8 * o8 + 4] * wb.x, xv[8 * o8 + 5] * wb.y); pk[3] = pk2(xv[8 * o8 + 6] * wb.z, xv[8 * o8 + 7] * wb.w);
;                     *(LAS v4u*)(dst + o8 * 16) = (v4u){pk[0], pk[1], pk[2], pk[3]}; } }
.LBB0_825:
	s_or_b64 exec, exec, s[4:5]
	v_lshlrev_b32_e32 v123, 2, v119
	s_waitcnt lgkmcnt(0)
	v_lshl_or_b32 v4, s64, 8, v123
	s_and_b64 s[0:1], s[36:37], exec
	v_add_u32_e32 v4, 0, v4
	s_cselect_b32 s0, 63, 0
	v_add_u32_e32 v5, 0x18c00, v4
	v_add_u32_e32 v4, 0x19400, v4
	v_cmp_eq_u32_e32 vcc, s0, v119
	ds_write_b32 v5, v2
	s_waitcnt vmcnt(0)
	ds_write_b32 v4, v3
	s_and_saveexec_b64 s[0:1], vcc
	s_lshl_b32 s3, s64, 2
	s_add_i32 s3, s3, 0
	s_add_i32 s3, s3, 0x19c00
	v_mov_b32_e32 v3, s3
	ds_write_b32 v3, v2
	s_or_b64 exec, exec, s[0:1]
	v_ashrrev_i32_e32 v10, 4, v82
	v_ashrrev_i32_e32 v11, 31, v10
	v_lshlrev_b32_e32 v6, 3, v82
	v_lshl_add_u64 v[2:3], s[6:7], 0, v[10:11]
	v_mad_u64_u32 v[4:5], s[0:1], v2, s42, v[112:113]
	v_and_b32_e32 v2, 64, v6
	v_and_b32_e32 v22, 0x78, v6
	v_add_u32_e32 v2, s34, v2
	v_mad_i32_i24 v5, v3, s42, v5
	v_add_lshl_u32 v110, v2, v22, 1
	v_lshl_add_u64 v[2:3], v[4:5], 0, v[110:111]
	v_add_u32_e32 v4, 0x200, v82
	v_ashrrev_i32_e32 v12, 4, v4
	v_ashrrev_i32_e32 v84, 8, v82
	v_ashrrev_i32_e32 v13, 31, v12
	v_lshlrev_b32_e32 v14, 5, v84
	v_lshl_add_u64 v[4:5], s[6:7], 0, v[12:13]
	v_ashrrev_i32_e32 v15, 31, v14
	v_mad_u64_u32 v[6:7], s[0:1], v4, s42, v[112:113]
	v_bfe_u32 v83, v82, 6, 2
	v_lshl_add_u64 v[14:15], s[6:7], 0, v[14:15]
	v_mad_i32_i24 v7, v5, s42, v7
	v_mad_u64_u32 v[16:17], s[0:1], v14, s42, v[112:113]
	v_or_b32_e32 v11, s31, v83
	v_lshl_add_u64 v[6:7], v[6:7], 0, v[110:111]
	v_mad_i32_i24 v17, v15, s42, v17
	v_lshlrev_b32_e32 v110, 7, v11
	v_lshl_add_u64 v[14:15], v[16:17], 0, v[110:111]
	v_lshlrev_b32_e32 v110, 1, v119
	v_lshlrev_b32_e32 v164, 1, v119
	v_lshl_add_u64 v[14:15], v[14:15], 0, v[110:111]
	s_nop 0
	v_readfirstlane_b32 s98, v14
	v_readfirstlane_b32 s99, v15
	s_nop 4
	global_load_dwordx4 v[2:5], v[2:3], off offset:1024
	global_load_dwordx4 v[6:9], v[6:7], off offset:1024
	v_lshlrev_b32_e32 v11, 4, v82
	global_load_ushort v85, v164, s[98:99]
	global_load_ushort v86, v164, s[98:99] offset:1536
	global_load_ushort v87, v164, s[98:99] offset:3072
	s_add_u32 s100, s98, s44
	s_addc_u32 s101, s99, 0
	global_load_ushort v88, v164, s[100:101] offset:512
	global_load_ushort v89, v164, s[100:101] offset:2048
	global_load_ushort v90, v164, s[100:101] offset:3584
	s_add_u32 s66, s98, s45
	s_addc_u32 s67, s99, 0
	global_load_ushort v91, v164, s[66:67] offset:1024
	global_load_ushort v92, v164, s[66:67] offset:2560
	v_and_b32_e32 v11, 0x70, v11
	v_mul_lo_u32 v10, v10, s43
	s_ashr_i32 s13, s64, 1
	s_add_u32 s70, s98, s46
	s_addc_u32 s71, s99, 0
	global_load_ushort v93, v164, s[70:71]
	global_load_ushort v94, v164, s[70:71] offset:1536
	global_load_ushort v95, v164, s[70:71] offset:3072
	s_add_u32 s100, s98, s47
	s_addc_u32 s101, s99, 0
	global_load_ushort v96, v164, s[100:101] offset:512
	global_load_ushort v97, v164, s[100:101] offset:2048
	global_load_ushort v98, v164, s[100:101] offset:3584
	s_add_u32 s66, s98, s50
	s_addc_u32 s67, s99, 0
	global_load_ushort v99, v164, s[66:67] offset:1024
	global_load_ushort v100, v164, s[66:67] offset:2560
	s_add_i32 s0, s13, s31
	s_lshl_b32 s1, s8, 4
	s_lshl_b32 s3, s0, 1
	s_add_u32 s70, s98, s51
	s_addc_u32 s71, s99, 0
	global_load_ushort v101, v164, s[70:71]
	global_load_ushort v102, v164, s[70:71] offset:1536
	global_load_ushort v103, v164, s[70:71] offset:3072
	s_add_u32 s100, s98, s52
	s_addc_u32 s101, s99, 0
	global_load_ushort v104, v164, s[100:101] offset:512
	global_load_ushort v105, v164, s[100:101] offset:2048
	global_load_ushort v106, v164, s[100:101] offset:3584
	s_add_u32 s66, s98, s53
	s_addc_u32 s67, s99, 0
	global_load_ushort v107, v164, s[66:67] offset:1024
	global_load_ushort v108, v164, s[66:67] offset:2560
	s_add_i32 s4, s3, s1
	s_ashr_i32 s5, s4, 31
	s_add_u32 s72, s98, s56
	s_addc_u32 s73, s99, 0
	v_and_b32_e32 v140, 15, v82
	s_add_u32 s70, s98, s54
	s_addc_u32 s71, s99, 0
	global_load_ushort v109, v164, s[70:71]
	global_load_ushort v121, v164, s[70:71] offset:1536
	global_load_ushort v144, v164, s[70:71] offset:3072
	s_add_u32 s100, s98, s55
	s_addc_u32 s101, s99, 0
	global_load_ushort v145, v164, s[100:101] offset:512
	global_load_ushort v146, v164, s[100:101] offset:2048
	global_load_ushort v147, v164, s[100:101] offset:3584
	global_load_ushort v148, v164, s[72:73] offset:1024
	global_load_ushort v149, v164, s[72:73] offset:2560
	v_cmp_gt_u32_e32 vcc, 64, v22
	s_lshl_b64 s[8:9], s[4:5], 13
	s_or_b32 s4, s4, 1
	v_cndmask_b32_e32 v13, 0, v1, vcc
	v_add3_u32 v10, v13, v10, v11
	s_ashr_i32 s5, s4, 31
	s_lshl_b64 s[4:5], s[4:5], 13
	s_and_b32 s12, s64, 1
	s_lshl_b32 s3, s12, 5
	v_or_b32_e32 v143, s3, v140
	v_or_b32_e32 v120, s6, v143
	v_lshrrev_b32_e32 v142, 4, v119
	v_lshlrev_b32_e32 v110, 3, v142
	v_or_b32_e32 v141, 16, v143
	v_or_b32_e32 v118, s6, v141
	s_ashr_i32 s1, s0, 31
	v_lshl_or_b32 v83, v83, 6, v119
	v_mul_u32_u24_e32 v83, 0x90, v83
	v_lshlrev_b32_e32 v84, 6, v84
	v_add3_u32 v83, 0, v83, v84
	v_mov_b32_e32 v150, 0
	v_mov_b32_e32 v153, 0
	s_waitcnt vmcnt(33)
	ds_write_b128 v10, v[2:5]
	v_mul_lo_u32 v2, v12, s43
	v_add3_u32 v2, v13, v2, v11
	s_waitcnt vmcnt(32)
; #define LAS __attribute__((address_space(3)))
; template <int PASS>
; __device__ __forceinline__ void ssd_unit(LAS unsigned char* lds, int ch, int g, const bf16* PROJ, const bf16* XBC, const float* At, const float* DTt, bf16* STS, float* DECS, bf16* OMIX,
;                                          const float* d_skip, const float* ssd_norm) {
;     ...
;             for (int jj = 0; jj < 32; ++jj) xv[jj] = xp[(size_t)jj * 768];
; #pragma unroll
;             for (int jj = 0; jj < 32; ++jj) asm volatile("" : "+v"(xv[jj]));
;             LAS unsigned char* dst = XT + (hl * 64 + p) * RS + half * 64;
; #pragma unroll
;             for (int o8 = 0; o8 < 4; ++o8) *(LAS v4u*)(dst + o8 * 16) = (v4u){xv[8 * o8] | (xv[8 * o8 + 1] << 16), xv[8 * o8 + 2] | (xv[8 * o8 + 3] << 16), xv[8 * o8 + 4] | (xv[8 * o8 + 5] << 16), xv[8 * o8 + 6] | (xv[8 * o8 + 7] << 16)};
;         }
;         const int hl = wave >> 1, ih = wave & 1, hh = 4 * g + hl;
;         bf16x8 sf[2][4][2];
; #pragma unroll
;         for (int d = 0; d < 2; ++d)
; #pragma unroll
;             for (int pt = 0; pt < 4; ++pt)
; #pragma unroll
;                 for (int ks = 0; ks < 2; ++ks) sf[d][pt][ks] = *(const bf16x8*)(STS + (size_t)((ch * 8 + hh) * 2 + d) * 4096 + (16 * pt + lr) * 64 + 32 * ks + 8 * lq);
;         v2u zz8[2][4];
; #pragma unroll
;         for (int i2 = 0; i2 < 2; ++i2)
; #pragma unroll
;             for (int pt = 0; pt < 4; ++pt) zz8[i2][pt] = *(const v2u*)(PROJ + (m0 + 16 * (2 * ih + i2) + lr) * LDP + PZ + hh * 64 + 16 * pt + 4 * lq);
;         const float ds_e = d_skip[hh];
;         f32x4 gn8[4];
; #pragma unroll
;         for (int pt = 0; pt < 4; ++pt) gn8[pt] = *(const f32x4*)(ssd_norm + 256 * g + 64 * hl + 16 * pt + 4 * lq);
;         __syncthreads();
;         {
;             const int ait = wave >> 1, i = 16 * ait + lr;
; #pragma unroll
;             for (int j2 = 0; j2 < 2; ++j2) { const int jt = 2 * (wave & 1) + j2, j0 = 16 * jt + 4 * lq; pg8::f32x4 cb = {0.f, 0.f, 0.f, 0.f};
;                 cb = MFMA16(ldsfrag(BM, 16 * jt + lr, 0, lq), ldsfrag(CM, 16 * ait + lr, 0, lq), cb); cb = MFMA16(ldsfrag(BM, 16 * jt + lr, 1, lq), ldsfrag(CM, 16 * ait + lr, 1, lq), cb);
; #pragma unroll
;                 for (int h4 = 0; h4 < 4; ++h4) { const float sfi = SC[h4 * 64 + i], sbi = SC[(4 + h4) * 64 + i]; float p[4];
	ds_write_b128 v2, v[6:9]
	v_and_b32_e32 v2, 48, v119
	v_mov_b32_e32 v3, v111
	v_lshl_add_u64 v[4:5], s[28:29], 0, v[2:3]
	v_lshl_add_u64 v[6:7], v[4:5], 0, s[8:9]
	v_lshlrev_b32_e32 v8, 7, v140
	v_mov_b32_e32 v9, v111
	v_lshl_add_u64 v[10:11], v[6:7], 0, v[8:9]
	s_waitcnt vmcnt(0)
	global_load_dwordx4 v[70:73], v[10:11], off
	global_load_dwordx4 v[46:49], v[10:11], off offset:64
	global_load_dwordx4 v[62:65], v[10:11], off offset:2048
	global_load_dwordx4 v[30:33], v[10:11], off offset:2112
	v_or_b32_e32 v10, 0x1000, v8
	v_mov_b32_e32 v11, v111
	v_lshl_add_u64 v[12:13], v[6:7], 0, v[10:11]
	global_load_dwordx4 v[54:57], v[12:13], off
	global_load_dwordx4 v[22:25], v[12:13], off offset:64
	v_or_b32_e32 v12, 0x1800, v8
	v_mov_b32_e32 v13, v111
	v_lshl_add_u64 v[6:7], v[6:7], 0, v[12:13]
	v_lshl_add_u64 v[4:5], v[4:5], 0, s[4:5]
	global_load_dwordx4 v[50:53], v[6:7], off
	global_load_dwordx4 v[18:21], v[6:7], off offset:64
	v_lshl_add_u64 v[6:7], v[4:5], 0, v[8:9]
	global_load_dwordx4 v[78:81], v[6:7], off
	global_load_dwordx4 v[42:45], v[6:7], off offset:64
	global_load_dwordx4 v[74:77], v[6:7], off offset:2048
	global_load_dwordx4 v[38:41], v[6:7], off offset:2112
	v_lshl_add_u64 v[6:7], v[4:5], 0, v[10:11]
	v_lshl_add_u64 v[4:5], v[4:5], 0, v[12:13]
	s_lshl_b32 s4, s0, 6
	global_load_dwordx4 v[66:69], v[6:7], off
	global_load_dwordx4 v[34:37], v[6:7], off offset:64
	global_load_dwordx4 v[58:61], v[4:5], off
	global_load_dwordx4 v[26:29], v[4:5], off offset:64
	s_ashr_i32 s5, s4, 31
	v_mad_u64_u32 v[4:5], s[8:9], v120, s57, v[114:115]
	v_mad_i32_i24 v5, s7, v117, v5
	s_lshl_b64 s[4:5], s[4:5], 1
	v_lshl_add_u64 v[4:5], v[4:5], 0, s[4:5]
	v_lshl_add_u64 v[4:5], v[4:5], 0, v[110:111]
	global_load_dwordx2 v[138:139], v[4:5], off offset:3072
	global_load_dwordx2 v[136:137], v[4:5], off offset:3104
	global_load_dwordx2 v[134:135], v[4:5], off offset:3136
	global_load_dwordx2 v[132:133], v[4:5], off offset:3168
	v_mad_u64_u32 v[4:5], s[8:9], v118, s57, v[114:115]
	s_lshl_b64 s[0:1], s[0:1], 2
	v_mad_i32_i24 v5, s7, v117, v5
	s_add_u32 s0, s48, s0
	v_lshl_add_u64 v[4:5], v[4:5], 0, s[4:5]
	s_addc_u32 s1, s49, s1
	s_lshl_b32 s36, s13, 6
	v_lshl_add_u64 v[4:5], v[4:5], 0, v[110:111]
	s_ashr_i32 s37, s36, 31
	global_load_dwordx2 v[130:131], v[4:5], off offset:3072
	global_load_dwordx2 v[128:129], v[4:5], off offset:3104
	global_load_dwordx2 v[126:127], v[4:5], off offset:3136
	global_load_dwordx2 v[124:125], v[4:5], off offset:3168
	global_load_dword v122, v111, s[0:1]
	s_lshl_b64 s[0:1], s[36:37], 2
	s_add_u32 s0, s40, s0
	s_addc_u32 s1, s41, s1
	global_load_dwordx4 v[14:17], v2, s[0:1]
	global_load_dwordx4 v[10:13], v2, s[0:1] offset:64
	global_load_dwordx4 v[6:9], v2, s[0:1] offset:128
	s_nop 0
	global_load_dwordx4 v[2:5], v2, s[0:1] offset:192
	v_lshl_or_b32 v84, v86, 16, v85
	v_lshl_or_b32 v85, v88, 16, v87
	v_lshl_or_b32 v86, v90, 16, v89
	v_lshl_or_b32 v87, v92, 16, v91
	ds_write_b128 v83, v[84:87] offset:27648
	v_lshl_or_b32 v84, v94, 16, v93
	v_lshl_or_b32 v85, v96, 16, v95
	v_lshl_or_b32 v86, v98, 16, v97
	v_lshl_or_b32 v87, v100, 16, v99
	ds_write_b128 v83, v[84:87] offset:27664
	v_lshl_or_b32 v84, v102, 16, v101
	v_lshl_or_b32 v85, v104, 16, v103
	v_lshl_or_b32 v86, v106, 16, v105
	v_lshl_or_b32 v87, v108, 16, v107
	ds_write_b128 v83, v[84:87] offset:27680
	v_lshl_or_b32 v84, v121, 16, v109
	v_lshl_or_b32 v85, v145, 16, v144
	v_lshl_or_b32 v86, v147, 16, v146
	v_lshl_or_b32 v87, v149, 16, v148
	v_and_b32_e32 v144, 48, v82
	v_mul_u32_u24_e32 v145, 0x90, v143
	ds_write_b128 v83, v[84:87] offset:27696
	v_add3_u32 v86, 0, v145, v144
	s_waitcnt lgkmcnt(0)
	s_barrier
	ds_read_b128 v[90:93], v86 offset:9216
	v_lshl_or_b32 v146, s13, 4, v140
	v_mul_lo_u32 v148, v146, s43
	v_add3_u32 v87, 0, v148, v144
	ds_read_b128 v[82:85], v87
	ds_read_b128 v[94:97], v86 offset:9280
	ds_read_b128 v[86:89], v87 offset:64
	s_waitcnt lgkmcnt(2)
	v_mfma_f32_16x16x32_bf16 v[90:93], v[90:93], v[82:85], 0
	v_lshlrev_b32_e32 v110, 2, v142
	v_or_b32_e32 v155, s3, v110
	s_add_i32 s3, 0, 0x18c00
	s_waitcnt lgkmcnt(0)
	v_mfma_f32_16x16x32_bf16 v[90:93], v[94:97], v[86:89], v[90:93]
	v_lshlrev_b32_e32 v94, 2, v155
	v_add_u32_e32 v95, 0, v94
	v_add_u32_e32 v158, s3, v94
	v_add_u32_e32 v156, 0x19400, v95
	v_lshlrev_b32_e32 v95, 2, v146
	v_add_u32_e32 v94, s58, v94
	v_add_u32_e32 v147, s3, v95
	v_add_u32_e32 v149, s58, v95
	ds_read_b128 v[94:97], v94
	ds_read_b128 v[106:109], v158
	ds_read_b128 v[102:105], v156
	ds_read_b32 v151, v147
	ds_read_b32 v152, v149
	ds_read_b128 v[98:101], v156 offset:1024
	s_lshl_b32 s26, s12, 1
	s_cmp_le_i32 s26, s13
	v_mov_b32_e32 v121, s7
	s_cselect_b64 s[0:1], -1, 0
	s_cmp_gt_i32 s26, s13
	v_cmp_le_i32_e32 vcc, v155, v146
	s_cbranch_scc1 .LBB0_829
	s_waitcnt lgkmcnt(2)
	v_sub_f32_e32 v106, v151, v106
	v_min_f32_e32 v106, 0, v106
	v_mul_f32_e32 v106, 0x3fb8aa3b, v106
	v_exp_f32_e32 v106, v106
	s_nop 0
	v_mul_f32_e32 v102, v102, v106
	v_cndmask_b32_e32 v153, 0, v102, vcc

; __device__ __forceinline__ unsigned xb_ld(unsigned* p)              { return __hip_atomic_load(p, __ATOMIC_RELAXED, __HIP_MEMORY_SCOPE_AGENT); }
; __device__ __forceinline__ unsigned xb_add(unsigned* p, unsigned v) { return __hip_atomic_fetch_add(p, v, __ATOMIC_RELAXED, __HIP_MEMORY_SCOPE_AGENT); }
; #define XB_SPIN(cond, bar) do { unsigned _sp = 0; while (cond) { __builtin_amdgcn_s_sleep(1); \
;     if ((++_sp & 255u) == 0u) { if (xb_ld(&(bar)[XB_TMO])) break; if (_sp > XB_SPIN_CAP) { atomicAdd(&(bar)[XB_TMO], 1u); break; } } } } while (0)
; __device__ __forceinline__ void xcd_barrier(const XcdBarrier& b) {
;     ...
;             __builtin_amdgcn_fence(__ATOMIC_RELEASE, "agent");
;             asm volatile("s_waitcnt vmcnt(0)" ::: "memory");
;             const unsigned og = xb_add(&bar[XB_TOP], 1u);
;             const unsigned tg = og / nx;
;             if (og + 1u == (tg + 1u) * nx) xb_add(&bar[XB_TOPGEN], 1u);
;             else XB_SPIN(xb_ld(&bar[XB_TOPGEN]) == tg, bar);
;             __builtin_amdgcn_fence(__ATOMIC_ACQUIRE, "agent");
;             xb_add(&bar[XB_XGEN(b.x)], 1u);
;             asm volatile("s_waitcnt vmcnt(0)" ::: "memory");
;         } else {
;             XB_SPIN(xb_ld(&bar[XB_XGEN(b.x)]) == gen, bar);
;             __builtin_amdgcn_fence(__ATOMIC_ACQUIRE, "agent");
;             asm volatile("s_waitcnt vmcnt(0)" ::: "memory");
.LBB0_990:
	s_or_b64 exec, exec, s[0:1]
	s_waitcnt vmcnt(0)
.LBB0_991:
	s_andn2_saveexec_b64 s[0:1], s[8:9]
	s_cbranch_execz .LBB0_1011
	s_mov_b64 s[0:1], exec
	buffer_wbl2 sc1
	s_waitcnt lgkmcnt(0)
	s_waitcnt vmcnt(0)
	buffer_inv sc1
	v_mbcnt_lo_u32_b32 v2, s0, 0
	v_mbcnt_hi_u32_b32 v2, s1, v2
	v_cmp_eq_u32_e32 vcc, 0, v2
	s_and_saveexec_b64 s[8:9], vcc
	s_cbranch_execz .LBB0_994
	s_bcnt1_i32_b64 s0, s[0:1]
	v_mov_b32_e32 v3, 0x7000
	v_mov_b32_e32 v4, s0
	global_atomic_add v3, v3, v4, s[78:79] offset:1024 sc0

; __device__ __forceinline__ unsigned xb_ld(unsigned* p)              { return __hip_atomic_load(p, __ATOMIC_RELAXED, __HIP_MEMORY_SCOPE_AGENT); }
; __device__ __forceinline__ unsigned xb_add(unsigned* p, unsigned v) { return __hip_atomic_fetch_add(p, v, __ATOMIC_RELAXED, __HIP_MEMORY_SCOPE_AGENT); }
; #define XB_SPIN(cond, bar) do { unsigned _sp = 0; while (cond) { __builtin_amdgcn_s_sleep(1); \
;     if ((++_sp & 255u) == 0u) { if (xb_ld(&(bar)[XB_TMO])) break; if (_sp > XB_SPIN_CAP) { atomicAdd(&(bar)[XB_TMO], 1u); break; } } } } while (0)
; __device__ __forceinline__ void xcd_barrier(const XcdBarrier& b) {
;     ...
;             __builtin_amdgcn_fence(__ATOMIC_RELEASE, "agent");
;             asm volatile("s_waitcnt vmcnt(0)" ::: "memory");
;             const unsigned og = xb_add(&bar[XB_TOP], 1u);
;             const unsigned tg = og / nx;
;             if (og + 1u == (tg + 1u) * nx) xb_add(&bar[XB_TOPGEN], 1u);
;             else XB_SPIN(xb_ld(&bar[XB_TOPGEN]) == tg, bar);
;             __builtin_amdgcn_fence(__ATOMIC_ACQUIRE, "agent");
;             xb_add(&bar[XB_XGEN(b.x)], 1u);
;             asm volatile("s_waitcnt vmcnt(0)" ::: "memory");
;         } else {
;             XB_SPIN(xb_ld(&bar[XB_XGEN(b.x)]) == gen, bar);
;             __builtin_amdgcn_fence(__ATOMIC_ACQUIRE, "agent");
;             asm volatile("s_waitcnt vmcnt(0)" ::: "memory");
.LBB0_1145:
	s_or_b64 exec, exec, s[0:1]
	s_waitcnt vmcnt(0)
.LBB0_1146:
	s_andn2_saveexec_b64 s[0:1], s[8:9]
	s_cbranch_execz .LBB0_1166
	s_mov_b64 s[0:1], exec
	buffer_wbl2 sc1
	s_waitcnt lgkmcnt(0)
	s_waitcnt vmcnt(0)
	buffer_inv sc1
	v_mbcnt_lo_u32_b32 v2, s0, 0
	v_mbcnt_hi_u32_b32 v2, s1, v2
	v_cmp_eq_u32_e32 vcc, 0, v2
	s_and_saveexec_b64 s[8:9], vcc
	s_cbranch_execz .LBB0_1149
	s_bcnt1_i32_b64 s0, s[0:1]
	v_mov_b32_e32 v3, 0x7000
	v_mov_b32_e32 v4, s0
	global_atomic_add v3, v3, v4, s[78:79] offset:1024 sc0

; __device__ __forceinline__ unsigned xb_ld(unsigned* p)              { return __hip_atomic_load(p, __ATOMIC_RELAXED, __HIP_MEMORY_SCOPE_AGENT); }
; __device__ __forceinline__ void xcd_barrier_complete(unsigned* bar, unsigned x, unsigned& nloc, unsigned& nx) {
;     const unsigned G = gridDim.x * gridDim.y * gridDim.z;
;     unsigned sum, cnt, mine, sp = 0u;
;     for (;;) {
;         sum = 0u; cnt = 0u; mine = 0u;
; #pragma unroll
;         for (unsigned j = 0; j < 16; ++j) { const unsigned c = xb_ld(&bar[XB_XCNT(j)]); sum += c; cnt += (c > 0u) ? 1u : 0u; mine = (j == x) ? c : mine; }
; __device__ __forceinline__ void xcd_barrier(const XcdBarrier& b) {
;     asm volatile("s_waitcnt vmcnt(0)" ::: "memory");
;     __syncthreads();
;     if (threadIdx.x == 0) {
;         unsigned* bar = b.bar;
;         __builtin_amdgcn_s_waitcnt(0);
;         unsigned nloc = b.st[0], nx = b.st[1];
;         if (nloc == 0u) { xcd_barrier_complete(bar, b.x, nloc, nx); b.st[0] = nloc; b.st[1] = nx; }
.LBB0_1186:
	s_waitcnt vmcnt(0)
	s_barrier
	s_and_saveexec_b64 s[4:5], s[96:97]
	s_cbranch_execz .LBB0_1238
	s_add_i32 s0, 0, 0x20160
	v_mov_b32_e32 v1, s0
	s_waitcnt vmcnt(0) expcnt(0) lgkmcnt(0)
	ds_read_b32 v3, v1
	s_add_i32 s0, 0, 0x20164
	v_mov_b32_e32 v1, s0
	ds_read_b32 v1, v1
	s_waitcnt lgkmcnt(1)
	v_cmp_ne_u32_e32 vcc, 0, v3
	s_cbranch_vccnz .LBB0_1202
	s_load_dwordx2 s[12:13], s[94:95], 0xf0
	s_load_dword s3, s[94:95], 0xf8
	s_add_u32 s0, s78, 0x4200
	s_addc_u32 s1, s79, 0
	s_add_u32 s6, s78, 0x4400
	s_waitcnt lgkmcnt(0)
	s_mul_i32 s7, s13, s12
	s_mul_i32 s3, s7, s3
	s_addc_u32 s7, s79, 0
	s_add_u32 s12, s78, 0x4500
	s_addc_u32 s13, s79, 0
	s_add_u32 s14, s78, 0x4600
	s_addc_u32 s15, s79, 0
	s_add_u32 s16, s78, 0x4700
	s_addc_u32 s17, s79, 0
	s_add_u32 s20, s78, 0x4800
	s_addc_u32 s21, s79, 0
	s_add_u32 s24, s78, 0x4900
	s_addc_u32 s25, s79, 0
	s_add_u32 s26, s78, 0x4a00
	s_addc_u32 s27, s79, 0
	s_add_u32 s28, s78, 0x4b00
	s_addc_u32 s29, s79, 0
	s_add_u32 s30, s78, 0x4c00
	s_addc_u32 s31, s79, 0
	s_add_u32 s36, s78, 0x4d00
	s_addc_u32 s37, s79, 0
	s_add_u32 s38, s78, 0x4e00
	s_addc_u32 s39, s79, 0
	s_add_u32 s40, s78, 0x4f00
	s_addc_u32 s41, s79, 0
	s_add_u32 s42, s78, 0x5000
	s_addc_u32 s43, s79, 0
	s_add_u32 s44, s78, 0x5100
	s_addc_u32 s45, s79, 0
	s_add_u32 s46, s78, 0x5200
	s_addc_u32 s47, s79, 0
	s_add_u32 s48, s78, 0x5300
	s_addc_u32 s49, s79, 0
	s_mov_b32 s54, 1
	v_mov_b32_e32 v17, 0
	s_branch .LBB0_1190

; __device__ __forceinline__ unsigned xb_ld(unsigned* p)              { return __hip_atomic_load(p, __ATOMIC_RELAXED, __HIP_MEMORY_SCOPE_AGENT); }
; __device__ __forceinline__ unsigned xb_add(unsigned* p, unsigned v) { return __hip_atomic_fetch_add(p, v, __ATOMIC_RELAXED, __HIP_MEMORY_SCOPE_AGENT); }
; #define XB_SPIN(cond, bar) do { unsigned _sp = 0; while (cond) { __builtin_amdgcn_s_sleep(1); \
;     if ((++_sp & 255u) == 0u) { if (xb_ld(&(bar)[XB_TMO])) break; if (_sp > XB_SPIN_CAP) { atomicAdd(&(bar)[XB_TMO], 1u); break; } } } } while (0)
; __device__ __forceinline__ void xcd_barrier(const XcdBarrier& b) {
;     ...
;             __builtin_amdgcn_fence(__ATOMIC_RELEASE, "agent");
;             asm volatile("s_waitcnt vmcnt(0)" ::: "memory");
;             const unsigned og = xb_add(&bar[XB_TOP], 1u);
;             const unsigned tg = og / nx;
;             if (og + 1u == (tg + 1u) * nx) xb_add(&bar[XB_TOPGEN], 1u);
;             else XB_SPIN(xb_ld(&bar[XB_TOPGEN]) == tg, bar);
;             __builtin_amdgcn_fence(__ATOMIC_ACQUIRE, "agent");
;             xb_add(&bar[XB_XGEN(b.x)], 1u);
;             asm volatile("s_waitcnt vmcnt(0)" ::: "memory");
;         } else {
;             XB_SPIN(xb_ld(&bar[XB_XGEN(b.x)]) == gen, bar);
;             __builtin_amdgcn_fence(__ATOMIC_ACQUIRE, "agent");
;             asm volatile("s_waitcnt vmcnt(0)" ::: "memory");
.LBB0_1217:
	s_or_b64 exec, exec, s[12:13]
	s_waitcnt vmcnt(0)
.LBB0_1218:
	s_andn2_saveexec_b64 s[6:7], s[6:7]
	s_cbranch_execz .LBB0_1238
	s_mov_b64 s[6:7], exec
	buffer_wbl2 sc1
	s_waitcnt lgkmcnt(0)
	s_waitcnt vmcnt(0)
	buffer_inv sc1
	v_mbcnt_lo_u32_b32 v2, s6, 0
	v_mbcnt_hi_u32_b32 v2, s7, v2
	v_cmp_eq_u32_e32 vcc, 0, v2
	s_and_saveexec_b64 s[12:13], vcc
	s_cbranch_execz .LBB0_1221
	s_bcnt1_i32_b64 s3, s[6:7]
	v_mov_b32_e32 v3, 0x7000
	v_mov_b32_e32 v4, s3
	global_atomic_add v3, v3, v4, s[78:79] offset:1024 sc0
